# MoBA gate: branch-free running top-3 insert (3 compares + 10 selects, state in place) instead of nested exec-masked branches + register rotation
# speedup vs baseline: 1.0034x; 1.0034x over previous
.LBB0_517:
	ds_read_b128 v[44:47], v18
	ds_read_b128 v[48:51], v18 offset:16
	ds_read_b128 v[52:55], v18 offset:32
	ds_read_b128 v[56:59], v18 offset:48
	ds_read_b128 v[60:63], v18 offset:64
	s_waitcnt lgkmcnt(4)
	v_fma_f32 v64, v44, v21, 0
	v_fmac_f32_e32 v64, v45, v22
	v_fmac_f32_e32 v64, v46, v23
	v_fmac_f32_e32 v64, v47, v24
	s_waitcnt lgkmcnt(3)
	v_fmac_f32_e32 v64, v48, v25
	v_fmac_f32_e32 v64, v49, v26
	v_fmac_f32_e32 v64, v50, v27
	v_fmac_f32_e32 v64, v51, v28
	s_waitcnt lgkmcnt(2)
	v_fmac_f32_e32 v64, v52, v29
	v_fmac_f32_e32 v64, v53, v30
	v_fmac_f32_e32 v64, v54, v31
	v_fmac_f32_e32 v64, v55, v32
	s_waitcnt lgkmcnt(1)
	v_fmac_f32_e32 v64, v56, v33
	v_fmac_f32_e32 v64, v57, v34
	v_fmac_f32_e32 v64, v58, v35
	ds_read_b128 v[44:47], v18 offset:80
	ds_read_b128 v[48:51], v18 offset:96
	v_fmac_f32_e32 v64, v59, v36
	s_waitcnt lgkmcnt(2)
	v_fmac_f32_e32 v64, v60, v38
	v_fmac_f32_e32 v64, v61, v39
	v_fmac_f32_e32 v64, v62, v40
	v_fmac_f32_e32 v64, v63, v41
	s_waitcnt lgkmcnt(1)
	v_pk_mul_f32 v[44:45], v[44:45], v[2:3]
	s_waitcnt lgkmcnt(0)
	v_pk_mul_f32 v[48:49], v[48:49], v[8:9]
	v_add_f32_e32 v44, v64, v44
	v_add_f32_e32 v52, v44, v45
	v_pk_mul_f32 v[44:45], v[46:47], v[6:7]
	s_nop 0
	v_add_f32_e32 v44, v52, v44
	v_add_f32_e32 v52, v44, v45
	ds_read_b128 v[44:47], v18 offset:112
	v_add_f32_e32 v48, v52, v48
	v_add_f32_e32 v52, v48, v49
	v_pk_mul_f32 v[48:49], v[50:51], v[10:11]
	s_waitcnt lgkmcnt(0)
	v_pk_mul_f32 v[44:45], v[44:45], v[12:13]
	v_add_f32_e32 v48, v52, v48
	v_add_f32_e32 v48, v48, v49
	v_add_f32_e32 v44, v48, v44
	v_add_f32_e32 v48, v44, v45
	v_pk_mul_f32 v[44:45], v[46:47], v[14:15]
	s_nop 0
	v_add_f32_e32 v44, v48, v44
	v_add_f32_e32 v44, v44, v45
	s_nop 1
	v_add_f32_dpp v44, v44, v44 quad_perm:[1,0,3,2] row_mask:0xf bank_mask:0xf
	v_cmp_gt_f32_e64 s[2:3], v44, v43
	v_cmp_gt_f32_e64 s[8:9], v44, v19
	v_cmp_gt_f32_e64 s[10:11], v44, v42
	v_mov_b32_e32 v45, s4
	s_nop 0
	v_cndmask_b32_e64 v46, v42, v44, s[10:11]
	v_cndmask_b32_e64 v47, v37, v45, s[10:11]
	v_cndmask_b32_e64 v42, v46, v19, s[8:9]
	v_cndmask_b32_e64 v37, v47, v5, s[8:9]
	v_cndmask_b32_e64 v46, v19, v44, s[8:9]
	v_cndmask_b32_e64 v47, v5, v45, s[8:9]
	v_cndmask_b32_e64 v19, v46, v43, s[2:3]
	v_cndmask_b32_e64 v5, v47, v0, s[2:3]
	v_cndmask_b32_e64 v43, v43, v44, s[2:3]
	v_cndmask_b32_e64 v0, v0, v45, s[2:3]
	s_add_i32 s4, s4, 1
	s_cmp_eq_u32 s23, s4
	v_add_u32_e32 v18, 0x100, v18
	s_cbranch_scc0 .LBB0_517
	v_mov_b32_e32 v45, v0
	v_mov_b32_e32 v0, v5
	v_mov_b32_e32 v5, v37
